# P0 xprep: the row's 8 loads issued together, rounds keep order with counted waits (was 4 dependent load+store-drain round trips per row)
# baseline (speedup 1.0000x reference)
.LBB0_20:
	s_cmpk_gt_i32 s90, 0xff
	s_mov_b64 s[0:1], -1
	s_cbranch_scc0 .LBB0_51
	s_cmpk_gt_u32 s90, 0x12ff
	s_cbranch_scc0 .LBB0_25
	v_mov_b32_e32 v0, v194
	s_lshl_b32 s0, s90, 3
	s_add_i32 s0, s0, 0xffff6800
	v_ashrrev_i32_e32 v0, 6, v0
	v_mov_b32_e32 v1, v194
	v_add_u32_e32 v0, s0, v0
	v_readlane_b32 s0, v230, 1
	v_and_b32_e32 v4, 63, v1
	v_ashrrev_i32_e32 v1, 31, v0
	s_waitcnt lgkmcnt(0)
	v_lshlrev_b64 v[2:3], 13, v[0:1]
	v_lshl_add_u64 v[2:3], s[36:37], 0, v[2:3]
	v_lshlrev_b32_e32 v32, 5, v4
	v_lshlrev_b64 v[6:7], 12, v[0:1]
	v_readlane_b32 s1, v230, 2
	v_lshl_add_u64 v[16:17], v[2:3], 0, v[32:33]
	v_cmp_lt_i32_e32 vcc, v60, v59
	v_lshl_add_u64 v[14:15], s[0:1], 0, v[6:7]
	global_load_dwordx4 v[6:9], v[16:17], off offset:16
	global_load_dwordx4 v[10:13], v[16:17], off
	v_or_b32_e32 v206, 0x1000, v32
	v_mov_b32_e32 v207, v33
	v_lshl_add_u64 v[204:205], v[2:3], 0, v[206:207]
	global_load_dwordx4 v[232:235], v[16:17], off offset:2064
	global_load_dwordx4 v[236:239], v[16:17], off offset:2048
	global_load_dwordx4 v[240:243], v[204:205], off offset:16
	global_load_dwordx4 v[244:247], v[204:205], off
	global_load_dwordx4 v[248:251], v[204:205], off offset:2064
	global_load_dwordx4 v[252:255], v[204:205], off offset:2048
	s_waitcnt vmcnt(6)
	v_mul_f32_e32 v5, v11, v11
	v_fmac_f32_e32 v5, v10, v10
	v_fmac_f32_e32 v5, v12, v12
	v_fmac_f32_e32 v5, v13, v13
	v_fmac_f32_e32 v5, v6, v6
	v_fmac_f32_e32 v5, v7, v7
	v_cvt_pk_bf16_f32 v10, v10, v11
	v_cvt_pk_bf16_f32 v11, v12, v13
	v_cvt_pk_bf16_f32 v12, v6, v7
	v_lshlrev_b32_e32 v6, 4, v4
	v_mov_b32_e32 v7, v33
	v_cvt_pk_bf16_f32 v13, v8, v9
	v_lshl_add_u64 v[14:15], v[14:15], 0, v[6:7]
	v_fmac_f32_e32 v5, v8, v8
	global_store_dwordx4 v[14:15], v[10:13], off
	v_fmac_f32_e32 v5, v9, v9
	s_waitcnt vmcnt(5)
	v_mul_f32_e32 v16, v237, v237
	v_fmac_f32_e32 v16, v236, v236
	v_fmac_f32_e32 v16, v238, v238
	v_fmac_f32_e32 v16, v239, v239
	v_fmac_f32_e32 v16, v232, v232
	v_fmac_f32_e32 v16, v233, v233
	v_cvt_pk_bf16_f32 v10, v236, v237
	v_cvt_pk_bf16_f32 v11, v238, v239
	v_cvt_pk_bf16_f32 v12, v232, v233
	v_cvt_pk_bf16_f32 v13, v234, v235
	v_or_b32_e32 v6, 0x1000, v32
	v_mov_b32_e32 v7, v33
	v_fmac_f32_e32 v16, v234, v234
	global_store_dwordx4 v[14:15], v[10:13], off offset:1024
	v_fmac_f32_e32 v16, v235, v235
	v_add_f32_e32 v5, v5, v16
	v_lshl_add_u64 v[10:11], v[2:3], 0, v[6:7]
	s_nop 0
	v_or_b32_e32 v32, 0x1800, v32
	v_lshl_add_u64 v[2:3], v[2:3], 0, v[32:33]
	s_waitcnt vmcnt(4)
	v_mul_f32_e32 v16, v245, v245
	v_fmac_f32_e32 v16, v244, v244
	v_fmac_f32_e32 v16, v246, v246
	v_fmac_f32_e32 v16, v247, v247
	v_fmac_f32_e32 v16, v240, v240
	v_fmac_f32_e32 v16, v241, v241
	v_cvt_pk_bf16_f32 v10, v244, v245
	v_cvt_pk_bf16_f32 v11, v246, v247
	v_cvt_pk_bf16_f32 v12, v240, v241
	v_cvt_pk_bf16_f32 v13, v242, v243
	v_fmac_f32_e32 v16, v242, v242
	global_store_dwordx4 v[14:15], v[10:13], off offset:2048
	v_fmac_f32_e32 v16, v243, v243
	v_add_f32_e32 v5, v5, v16
	v_cndmask_b32_e32 v3, v58, v60, vcc
	v_lshlrev_b32_e32 v3, 2, v3
	v_cmp_lt_i32_e32 vcc, v61, v59
	s_waitcnt vmcnt(3)
	v_mul_f32_e32 v2, v253, v253
	v_fmac_f32_e32 v2, v252, v252
	v_fmac_f32_e32 v2, v254, v254
	v_fmac_f32_e32 v2, v255, v255
	v_fmac_f32_e32 v2, v248, v248
	v_fmac_f32_e32 v2, v249, v249
	v_fmac_f32_e32 v2, v250, v250
	v_fmac_f32_e32 v2, v251, v251
	v_add_f32_e32 v2, v5, v2
	ds_bpermute_b32 v3, v3, v2
	v_cvt_pk_bf16_f32 v10, v252, v253
	v_cvt_pk_bf16_f32 v11, v254, v255
	v_cvt_pk_bf16_f32 v12, v248, v249
	v_cvt_pk_bf16_f32 v13, v250, v251
	s_waitcnt lgkmcnt(0)
	v_add_f32_e32 v2, v2, v3
	v_cndmask_b32_e32 v3, v58, v61, vcc
	v_lshlrev_b32_e32 v3, 2, v3
	ds_bpermute_b32 v3, v3, v2
	v_cmp_lt_i32_e32 vcc, v62, v59
	global_store_dwordx4 v[14:15], v[10:13], off offset:3072
	s_waitcnt lgkmcnt(0)
	v_add_f32_e32 v2, v2, v3
	v_cndmask_b32_e32 v3, v58, v62, vcc
	v_lshlrev_b32_e32 v3, 2, v3
	ds_bpermute_b32 v3, v3, v2
	v_cmp_lt_i32_e32 vcc, v63, v59
	s_waitcnt lgkmcnt(0)
	v_add_f32_e32 v2, v2, v3
	v_cndmask_b32_e32 v3, v58, v63, vcc
	v_lshlrev_b32_e32 v3, 2, v3
	ds_bpermute_b32 v3, v3, v2
	v_cmp_lt_i32_e32 vcc, v64, v59
	s_waitcnt lgkmcnt(0)
	v_add_f32_e32 v2, v2, v3
	v_cndmask_b32_e32 v3, v58, v64, vcc
	v_lshlrev_b32_e32 v3, 2, v3
	ds_bpermute_b32 v3, v3, v2
	v_cmp_lt_i32_e32 vcc, v65, v59
	s_waitcnt lgkmcnt(0)
	v_add_f32_e32 v2, v2, v3
	v_cndmask_b32_e32 v3, v58, v65, vcc
	v_lshlrev_b32_e32 v3, 2, v3
	ds_bpermute_b32 v3, v3, v2
	v_cmp_eq_u32_e32 vcc, 0, v4
	s_and_saveexec_b64 s[0:1], vcc
	s_cbranch_execz .LBB0_24
	s_waitcnt lgkmcnt(0)
	v_add_f32_e32 v2, v2, v3
	v_fmamk_f32 v2, v2, 0x3a000000, v55
	s_mov_b32 s4, 0x800000
	v_mul_f32_e32 v3, 0x4b800000, v2
	v_cmp_gt_f32_e32 vcc, s4, v2
	s_mov_b32 s3, s31
	v_readlane_b32 s28, v230, 3
	v_cndmask_b32_e32 v2, v2, v3, vcc
	v_rsq_f32_e32 v2, v2
	v_readlane_b32 s29, v230, 4
	v_readlane_b32 s31, v230, 6
	s_mov_b32 s31, s3
	v_mul_f32_e32 v3, 0x45800000, v2
	v_cndmask_b32_e32 v2, v2, v3, vcc
	v_lshl_add_u64 v[0:1], v[0:1], 2, s[28:29]
	v_readlane_b32 s30, v230, 5
	global_store_dword v[0:1], v2, off
